# grid barrier in-loop copies: non-leader workgroups poll the cross-XCD release word directly, leaders no longer re-publish per XCD; on top of v45 (hyena prefetch+pipelined loop, tile-local final, atten
# speedup vs baseline: 1.0070x; 1.0005x over previous
; __device__ __forceinline__ unsigned xb_ld(unsigned* p)              { return __hip_atomic_load(p, __ATOMIC_RELAXED, __HIP_MEMORY_SCOPE_AGENT); }
; __device__ __forceinline__ unsigned xb_add(unsigned* p, unsigned v) { return __hip_atomic_fetch_add(p, v, __ATOMIC_RELAXED, __HIP_MEMORY_SCOPE_AGENT); }
; #define XB_SPIN(cond, bar) do { unsigned _sp = 0; while (cond) { __builtin_amdgcn_s_sleep(1); \
;     if ((++_sp & 255u) == 0u) { if (xb_ld(&(bar)[XB_TMO])) break; if (_sp > XB_SPIN_CAP) { atomicAdd(&(bar)[XB_TMO], 1u); break; } } } } while (0)
; __device__ __forceinline__ void xcd_barrier(const XcdBarrier& b) {
;     ...
;         if (old + 1u == (gen + 1u) * nloc) {
;             __builtin_amdgcn_fence(__ATOMIC_RELEASE, "agent");
;             asm volatile("s_waitcnt vmcnt(0)" ::: "memory");
;             const unsigned og = xb_add(&bar[XB_TOP], 1u);
;             const unsigned tg = og / nx;
;             if (og + 1u == (tg + 1u) * nx) xb_add(&bar[XB_TOPGEN], 1u);
;             else XB_SPIN(xb_ld(&bar[XB_TOPGEN]) == tg, bar);
;             __builtin_amdgcn_fence(__ATOMIC_ACQUIRE, "agent");
;             xb_add(&bar[XB_XGEN(b.x)], 1u);
;             asm volatile("s_waitcnt vmcnt(0)" ::: "memory");
.LBB0_167:
	s_or_b64 exec, exec, s[16:17]
	s_waitcnt vmcnt(0)
	buffer_inv sc1
	s_waitcnt vmcnt(0)

; __device__ __forceinline__ unsigned xb_ld(unsigned* p)              { return __hip_atomic_load(p, __ATOMIC_RELAXED, __HIP_MEMORY_SCOPE_AGENT); }
; __device__ __forceinline__ unsigned xb_add(unsigned* p, unsigned v) { return __hip_atomic_fetch_add(p, v, __ATOMIC_RELAXED, __HIP_MEMORY_SCOPE_AGENT); }
; #define XB_SPIN(cond, bar) do { unsigned _sp = 0; while (cond) { __builtin_amdgcn_s_sleep(1); \
;     if ((++_sp & 255u) == 0u) { if (xb_ld(&(bar)[XB_TMO])) break; if (_sp > XB_SPIN_CAP) { atomicAdd(&(bar)[XB_TMO], 1u); break; } } } } while (0)
; __device__ __forceinline__ void xcd_barrier(const XcdBarrier& b) {
;     ...
;         const unsigned old = xb_add(&bar[XB_XSUB(b.x)], 1u);
;         const unsigned gen = old / nloc;
;         if (old + 1u == (gen + 1u) * nloc) {
;             __builtin_amdgcn_fence(__ATOMIC_RELEASE, "agent");
;             asm volatile("s_waitcnt vmcnt(0)" ::: "memory");
;             const unsigned og = xb_add(&bar[XB_TOP], 1u);
;             const unsigned tg = og / nx;
;             if (og + 1u == (tg + 1u) * nx) xb_add(&bar[XB_TOPGEN], 1u);
;             else XB_SPIN(xb_ld(&bar[XB_TOPGEN]) == tg, bar);
;             __builtin_amdgcn_fence(__ATOMIC_ACQUIRE, "agent");
;             xb_add(&bar[XB_XGEN(b.x)], 1u);
;             asm volatile("s_waitcnt vmcnt(0)" ::: "memory");
;         } else {
;             XB_SPIN(xb_ld(&bar[XB_XGEN(b.x)]) == gen, bar);
.LBB0_190:
	global_atomic_add v4, v[190:191], v220, off sc0
	v_cvt_f32_u32_e32 v2, v3
	v_sub_u32_e32 v5, 0, v3
	v_rcp_iflag_f32_e32 v2, v2
	s_nop 0
	v_mul_f32_e32 v2, 0x4f7ffffe, v2
	v_cvt_u32_f32_e32 v2, v2
	v_mul_lo_u32 v5, v5, v2
	v_mul_hi_u32 v5, v2, v5
	v_add_u32_e32 v2, v2, v5
	s_waitcnt vmcnt(0)
	v_mul_hi_u32 v2, v4, v2
	v_mul_lo_u32 v5, v2, v3
	v_sub_u32_e32 v5, v4, v5
	v_add_u32_e32 v6, 1, v2
	v_sub_u32_e32 v7, v5, v3
	v_cmp_ge_u32_e32 vcc, v5, v3
	v_add_u32_e32 v4, 1, v4
	s_nop 0
	v_cndmask_b32_e32 v2, v2, v6, vcc
	v_cndmask_b32_e32 v5, v5, v7, vcc
	v_add_u32_e32 v6, 1, v2
	v_cmp_ge_u32_e32 vcc, v5, v3
	s_nop 1
	v_cndmask_b32_e32 v2, v2, v6, vcc
	v_mul_lo_u32 v5, v3, v2
	v_add_u32_e32 v3, v5, v3
	v_cmp_ne_u32_e32 vcc, v4, v3
	s_and_saveexec_b64 s[2:3], vcc
	s_xor_b64 s[16:17], exec, s[2:3]
	s_cbranch_execz .LBB0_204
	s_waitcnt lgkmcnt(0)
	v_readlane_b32 s98, v247, 3
	v_readlane_b32 s99, v247, 4
	s_nop 4
	global_load_dword v0, v1, s[98:99] sc1
	s_waitcnt vmcnt(0)
	v_cmp_eq_u32_e32 vcc, v0, v2
	s_and_saveexec_b64 s[34:35], vcc
	s_cbranch_execz .LBB0_203
	s_mov_b32 s2, 1
	s_mov_b64 s[40:41], 0
	s_branch .LBB0_194

; __device__ __forceinline__ unsigned xb_ld(unsigned* p)              { return __hip_atomic_load(p, __ATOMIC_RELAXED, __HIP_MEMORY_SCOPE_AGENT); }
; #define XB_SPIN(cond, bar) do { unsigned _sp = 0; while (cond) { __builtin_amdgcn_s_sleep(1); \
;     if ((++_sp & 255u) == 0u) { if (xb_ld(&(bar)[XB_TMO])) break; if (_sp > XB_SPIN_CAP) { atomicAdd(&(bar)[XB_TMO], 1u); break; } } } } while (0)
; __device__ __forceinline__ void xcd_barrier(const XcdBarrier& b) {
;     ...
;             XB_SPIN(xb_ld(&bar[XB_XGEN(b.x)]) == gen, bar);
;             __builtin_amdgcn_fence(__ATOMIC_ACQUIRE, "agent");
.LBB0_196:
	global_load_dword v0, v1, s[98:99] sc1
	s_add_i32 s2, s2, 1
	s_mov_b64 s[46:47], -1
	s_waitcnt vmcnt(0)
	v_cmp_ne_u32_e32 vcc, v0, v2
	s_orn2_b64 s[44:45], vcc, exec
	s_branch .LBB0_193

; __device__ __forceinline__ unsigned xb_ld(unsigned* p)              { return __hip_atomic_load(p, __ATOMIC_RELAXED, __HIP_MEMORY_SCOPE_AGENT); }
; __device__ __forceinline__ unsigned xb_add(unsigned* p, unsigned v) { return __hip_atomic_fetch_add(p, v, __ATOMIC_RELAXED, __HIP_MEMORY_SCOPE_AGENT); }
; #define XB_SPIN(cond, bar) do { unsigned _sp = 0; while (cond) { __builtin_amdgcn_s_sleep(1); \
;     if ((++_sp & 255u) == 0u) { if (xb_ld(&(bar)[XB_TMO])) break; if (_sp > XB_SPIN_CAP) { atomicAdd(&(bar)[XB_TMO], 1u); break; } } } } while (0)
; __device__ __forceinline__ void xcd_barrier(const XcdBarrier& b) {
;     ...
;             if (og + 1u == (tg + 1u) * nx) xb_add(&bar[XB_TOPGEN], 1u);
;             else XB_SPIN(xb_ld(&bar[XB_TOPGEN]) == tg, bar);
;             __builtin_amdgcn_fence(__ATOMIC_ACQUIRE, "agent");
;             xb_add(&bar[XB_XGEN(b.x)], 1u);
;             asm volatile("s_waitcnt vmcnt(0)" ::: "memory");
.LBB0_219:
	s_or_b64 exec, exec, s[34:35]
	s_and_saveexec_b64 s[34:35], s[40:41]
	s_cbranch_execz .LBB0_221
	global_atomic_add v[2:3], v220, off
.LBB0_221:
	s_or_b64 exec, exec, s[34:35]
	s_waitcnt vmcnt(0)
	buffer_inv sc1
	s_waitcnt vmcnt(0)
.LBB0_222:
	s_or_b64 exec, exec, s[16:17]

; __device__ __forceinline__ unsigned xb_ld(unsigned* p)              { return __hip_atomic_load(p, __ATOMIC_RELAXED, __HIP_MEMORY_SCOPE_AGENT); }
; __device__ __forceinline__ unsigned xb_add(unsigned* p, unsigned v) { return __hip_atomic_fetch_add(p, v, __ATOMIC_RELAXED, __HIP_MEMORY_SCOPE_AGENT); }
; #define XB_SPIN(cond, bar) do { unsigned _sp = 0; while (cond) { __builtin_amdgcn_s_sleep(1); \
;     if ((++_sp & 255u) == 0u) { if (xb_ld(&(bar)[XB_TMO])) break; if (_sp > XB_SPIN_CAP) { atomicAdd(&(bar)[XB_TMO], 1u); break; } } } } while (0)
; __device__ __forceinline__ void xcd_barrier(const XcdBarrier& b) {
;     ...
;         const unsigned old = xb_add(&bar[XB_XSUB(b.x)], 1u);
;         const unsigned gen = old / nloc;
;         if (old + 1u == (gen + 1u) * nloc) {
;             __builtin_amdgcn_fence(__ATOMIC_RELEASE, "agent");
;             asm volatile("s_waitcnt vmcnt(0)" ::: "memory");
;             const unsigned og = xb_add(&bar[XB_TOP], 1u);
;             const unsigned tg = og / nx;
;             if (og + 1u == (tg + 1u) * nx) xb_add(&bar[XB_TOPGEN], 1u);
;             else XB_SPIN(xb_ld(&bar[XB_TOPGEN]) == tg, bar);
;             __builtin_amdgcn_fence(__ATOMIC_ACQUIRE, "agent");
;             xb_add(&bar[XB_XGEN(b.x)], 1u);
;             asm volatile("s_waitcnt vmcnt(0)" ::: "memory");
;         } else {
;             XB_SPIN(xb_ld(&bar[XB_XGEN(b.x)]) == gen, bar);
.LBB0_295:
	global_atomic_add v4, v[190:191], v220, off sc0
	v_cvt_f32_u32_e32 v2, v3
	v_sub_u32_e32 v5, 0, v3
	v_rcp_iflag_f32_e32 v2, v2
	s_nop 0
	v_mul_f32_e32 v2, 0x4f7ffffe, v2
	v_cvt_u32_f32_e32 v2, v2
	v_mul_lo_u32 v5, v5, v2
	v_mul_hi_u32 v5, v2, v5
	v_add_u32_e32 v2, v2, v5
	s_waitcnt vmcnt(0)
	v_mul_hi_u32 v2, v4, v2
	v_mul_lo_u32 v5, v2, v3
	v_sub_u32_e32 v5, v4, v5
	v_add_u32_e32 v6, 1, v2
	v_sub_u32_e32 v7, v5, v3
	v_cmp_ge_u32_e32 vcc, v5, v3
	v_add_u32_e32 v4, 1, v4
	s_nop 0
	v_cndmask_b32_e32 v2, v2, v6, vcc
	v_cndmask_b32_e32 v5, v5, v7, vcc
	v_add_u32_e32 v6, 1, v2
	v_cmp_ge_u32_e32 vcc, v5, v3
	s_nop 1
	v_cndmask_b32_e32 v2, v2, v6, vcc
	v_mul_lo_u32 v5, v3, v2
	v_add_u32_e32 v3, v5, v3
	v_cmp_ne_u32_e32 vcc, v4, v3
	s_and_saveexec_b64 s[2:3], vcc
	s_xor_b64 s[34:35], exec, s[2:3]
	s_cbranch_execz .LBB0_309
	s_waitcnt lgkmcnt(0)
	v_readlane_b32 s98, v247, 3
	v_readlane_b32 s99, v247, 4
	s_nop 4
	global_load_dword v0, v1, s[98:99] sc1
	s_waitcnt vmcnt(0)
	v_cmp_eq_u32_e32 vcc, v0, v2
	s_and_saveexec_b64 s[40:41], vcc
	s_cbranch_execz .LBB0_308
	s_mov_b32 s2, 1
	s_mov_b64 s[42:43], 0
	s_branch .LBB0_299

; __device__ __forceinline__ unsigned xb_ld(unsigned* p)              { return __hip_atomic_load(p, __ATOMIC_RELAXED, __HIP_MEMORY_SCOPE_AGENT); }
; #define XB_SPIN(cond, bar) do { unsigned _sp = 0; while (cond) { __builtin_amdgcn_s_sleep(1); \
;     if ((++_sp & 255u) == 0u) { if (xb_ld(&(bar)[XB_TMO])) break; if (_sp > XB_SPIN_CAP) { atomicAdd(&(bar)[XB_TMO], 1u); break; } } } } while (0)
; __device__ __forceinline__ void xcd_barrier(const XcdBarrier& b) {
;     ...
;             XB_SPIN(xb_ld(&bar[XB_XGEN(b.x)]) == gen, bar);
;             __builtin_amdgcn_fence(__ATOMIC_ACQUIRE, "agent");
.LBB0_301:
	global_load_dword v0, v1, s[98:99] sc1
	s_add_i32 s2, s2, 1
	s_mov_b64 s[48:49], -1
	s_waitcnt vmcnt(0)
	v_cmp_ne_u32_e32 vcc, v0, v2
	s_orn2_b64 s[46:47], vcc, exec
	s_branch .LBB0_298

; __device__ __forceinline__ unsigned xb_ld(unsigned* p)              { return __hip_atomic_load(p, __ATOMIC_RELAXED, __HIP_MEMORY_SCOPE_AGENT); }
; __device__ __forceinline__ unsigned xb_add(unsigned* p, unsigned v) { return __hip_atomic_fetch_add(p, v, __ATOMIC_RELAXED, __HIP_MEMORY_SCOPE_AGENT); }
; #define XB_SPIN(cond, bar) do { unsigned _sp = 0; while (cond) { __builtin_amdgcn_s_sleep(1); \
;     if ((++_sp & 255u) == 0u) { if (xb_ld(&(bar)[XB_TMO])) break; if (_sp > XB_SPIN_CAP) { atomicAdd(&(bar)[XB_TMO], 1u); break; } } } } while (0)
; __device__ __forceinline__ void xcd_barrier(const XcdBarrier& b) {
;     ...
;             if (og + 1u == (tg + 1u) * nx) xb_add(&bar[XB_TOPGEN], 1u);
;             else XB_SPIN(xb_ld(&bar[XB_TOPGEN]) == tg, bar);
;             __builtin_amdgcn_fence(__ATOMIC_ACQUIRE, "agent");
;             xb_add(&bar[XB_XGEN(b.x)], 1u);
;             asm volatile("s_waitcnt vmcnt(0)" ::: "memory");
.LBB0_324:
	s_or_b64 exec, exec, s[40:41]
	s_and_saveexec_b64 s[40:41], s[42:43]
	s_cbranch_execz .LBB0_326
	global_atomic_add v[2:3], v220, off
.LBB0_326:
	s_or_b64 exec, exec, s[40:41]
	s_waitcnt vmcnt(0)
	buffer_inv sc1
	s_waitcnt vmcnt(0)
.LBB0_327:
	s_or_b64 exec, exec, s[34:35]

; __device__ __forceinline__ unsigned xb_ld(unsigned* p)              { return __hip_atomic_load(p, __ATOMIC_RELAXED, __HIP_MEMORY_SCOPE_AGENT); }
; __device__ __forceinline__ unsigned xb_add(unsigned* p, unsigned v) { return __hip_atomic_fetch_add(p, v, __ATOMIC_RELAXED, __HIP_MEMORY_SCOPE_AGENT); }
; #define XB_SPIN(cond, bar) do { unsigned _sp = 0; while (cond) { __builtin_amdgcn_s_sleep(1); \
;     if ((++_sp & 255u) == 0u) { if (xb_ld(&(bar)[XB_TMO])) break; if (_sp > XB_SPIN_CAP) { atomicAdd(&(bar)[XB_TMO], 1u); break; } } } } while (0)
; __device__ __forceinline__ void xcd_barrier(const XcdBarrier& b) {
;     ...
;         const unsigned old = xb_add(&bar[XB_XSUB(b.x)], 1u);
;         const unsigned gen = old / nloc;
;         if (old + 1u == (gen + 1u) * nloc) {
;             __builtin_amdgcn_fence(__ATOMIC_RELEASE, "agent");
;             asm volatile("s_waitcnt vmcnt(0)" ::: "memory");
;             const unsigned og = xb_add(&bar[XB_TOP], 1u);
;             const unsigned tg = og / nx;
;             if (og + 1u == (tg + 1u) * nx) xb_add(&bar[XB_TOPGEN], 1u);
;             else XB_SPIN(xb_ld(&bar[XB_TOPGEN]) == tg, bar);
;             __builtin_amdgcn_fence(__ATOMIC_ACQUIRE, "agent");
;             xb_add(&bar[XB_XGEN(b.x)], 1u);
;             asm volatile("s_waitcnt vmcnt(0)" ::: "memory");
;         } else {
;             XB_SPIN(xb_ld(&bar[XB_XGEN(b.x)]) == gen, bar);
.LBB0_568:
	global_atomic_add v4, v[190:191], v220, off sc0
	v_cvt_f32_u32_e32 v0, v3
	v_sub_u32_e32 v5, 0, v3
	v_rcp_iflag_f32_e32 v0, v0
	s_nop 0
	v_mul_f32_e32 v0, 0x4f7ffffe, v0
	v_cvt_u32_f32_e32 v0, v0
	v_mul_lo_u32 v5, v5, v0
	v_mul_hi_u32 v5, v0, v5
	v_add_u32_e32 v0, v0, v5
	s_waitcnt vmcnt(0)
	v_mul_hi_u32 v0, v4, v0
	v_mul_lo_u32 v5, v0, v3
	v_sub_u32_e32 v5, v4, v5
	v_add_u32_e32 v6, 1, v0
	v_cmp_ge_u32_e32 vcc, v5, v3
	v_add_u32_e32 v4, 1, v4
	s_nop 0
	v_cndmask_b32_e32 v0, v0, v6, vcc
	v_sub_u32_e32 v6, v5, v3
	v_cndmask_b32_e32 v5, v5, v6, vcc
	v_add_u32_e32 v6, 1, v0
	v_cmp_ge_u32_e32 vcc, v5, v3
	s_nop 1
	v_cndmask_b32_e32 v0, v0, v6, vcc
	v_mul_lo_u32 v5, v3, v0
	v_add_u32_e32 v3, v5, v3
	v_cmp_ne_u32_e32 vcc, v4, v3
	s_and_saveexec_b64 s[2:3], vcc
	s_xor_b64 s[34:35], exec, s[2:3]
	s_cbranch_execz .LBB0_582
	s_waitcnt lgkmcnt(0)
	v_readlane_b32 s98, v247, 3
	v_readlane_b32 s99, v247, 4
	s_nop 4
	global_load_dword v2, v1, s[98:99] sc1
	s_waitcnt vmcnt(0)
	v_cmp_eq_u32_e32 vcc, v2, v0
	s_and_saveexec_b64 s[40:41], vcc
	s_cbranch_execz .LBB0_581
	s_mov_b32 s2, 1
	s_mov_b64 s[42:43], 0
	s_branch .LBB0_572

; __device__ __forceinline__ unsigned xb_ld(unsigned* p)              { return __hip_atomic_load(p, __ATOMIC_RELAXED, __HIP_MEMORY_SCOPE_AGENT); }
; #define XB_SPIN(cond, bar) do { unsigned _sp = 0; while (cond) { __builtin_amdgcn_s_sleep(1); \
;     if ((++_sp & 255u) == 0u) { if (xb_ld(&(bar)[XB_TMO])) break; if (_sp > XB_SPIN_CAP) { atomicAdd(&(bar)[XB_TMO], 1u); break; } } } } while (0)
; __device__ __forceinline__ void xcd_barrier(const XcdBarrier& b) {
;     ...
;             XB_SPIN(xb_ld(&bar[XB_XGEN(b.x)]) == gen, bar);
;             __builtin_amdgcn_fence(__ATOMIC_ACQUIRE, "agent");
.LBB0_574:
	global_load_dword v2, v1, s[98:99] sc1
	s_add_i32 s2, s2, 1
	s_mov_b64 s[48:49], -1
	s_waitcnt vmcnt(0)
	v_cmp_ne_u32_e32 vcc, v2, v0
	s_orn2_b64 s[46:47], vcc, exec
	s_branch .LBB0_571

; __device__ __forceinline__ unsigned xb_ld(unsigned* p)              { return __hip_atomic_load(p, __ATOMIC_RELAXED, __HIP_MEMORY_SCOPE_AGENT); }
; __device__ __forceinline__ unsigned xb_add(unsigned* p, unsigned v) { return __hip_atomic_fetch_add(p, v, __ATOMIC_RELAXED, __HIP_MEMORY_SCOPE_AGENT); }
; #define XB_SPIN(cond, bar) do { unsigned _sp = 0; while (cond) { __builtin_amdgcn_s_sleep(1); \
;     if ((++_sp & 255u) == 0u) { if (xb_ld(&(bar)[XB_TMO])) break; if (_sp > XB_SPIN_CAP) { atomicAdd(&(bar)[XB_TMO], 1u); break; } } } } while (0)
; __device__ __forceinline__ void xcd_barrier(const XcdBarrier& b) {
;     ...
;             if (og + 1u == (tg + 1u) * nx) xb_add(&bar[XB_TOPGEN], 1u);
;             else XB_SPIN(xb_ld(&bar[XB_TOPGEN]) == tg, bar);
;             __builtin_amdgcn_fence(__ATOMIC_ACQUIRE, "agent");
;             xb_add(&bar[XB_XGEN(b.x)], 1u);
;             asm volatile("s_waitcnt vmcnt(0)" ::: "memory");
.LBB0_597:
	s_or_b64 exec, exec, s[40:41]
	s_and_saveexec_b64 s[40:41], s[42:43]
	s_cbranch_execz .LBB0_599
	global_atomic_add v[2:3], v220, off
.LBB0_599:
	s_or_b64 exec, exec, s[40:41]
	s_waitcnt vmcnt(0)
	buffer_inv sc1
	s_waitcnt vmcnt(0)
.LBB0_600:
	s_or_b64 exec, exec, s[34:35]

; __device__ __forceinline__ unsigned xb_ld(unsigned* p)              { return __hip_atomic_load(p, __ATOMIC_RELAXED, __HIP_MEMORY_SCOPE_AGENT); }
; __device__ __forceinline__ unsigned xb_add(unsigned* p, unsigned v) { return __hip_atomic_fetch_add(p, v, __ATOMIC_RELAXED, __HIP_MEMORY_SCOPE_AGENT); }
; #define XB_SPIN(cond, bar) do { unsigned _sp = 0; while (cond) { __builtin_amdgcn_s_sleep(1); \
;     if ((++_sp & 255u) == 0u) { if (xb_ld(&(bar)[XB_TMO])) break; if (_sp > XB_SPIN_CAP) { atomicAdd(&(bar)[XB_TMO], 1u); break; } } } } while (0)
; __device__ __forceinline__ void xcd_barrier(const XcdBarrier& b) {
;     ...
;         const unsigned old = xb_add(&bar[XB_XSUB(b.x)], 1u);
;         const unsigned gen = old / nloc;
;         if (old + 1u == (gen + 1u) * nloc) {
;             __builtin_amdgcn_fence(__ATOMIC_RELEASE, "agent");
;             asm volatile("s_waitcnt vmcnt(0)" ::: "memory");
;             const unsigned og = xb_add(&bar[XB_TOP], 1u);
;             const unsigned tg = og / nx;
;             if (og + 1u == (tg + 1u) * nx) xb_add(&bar[XB_TOPGEN], 1u);
;             else XB_SPIN(xb_ld(&bar[XB_TOPGEN]) == tg, bar);
;             __builtin_amdgcn_fence(__ATOMIC_ACQUIRE, "agent");
;             xb_add(&bar[XB_XGEN(b.x)], 1u);
;             asm volatile("s_waitcnt vmcnt(0)" ::: "memory");
;         } else {
;             XB_SPIN(xb_ld(&bar[XB_XGEN(b.x)]) == gen, bar);
.LBB0_632:
	global_atomic_add v4, v[190:191], v220, off sc0
	v_cvt_f32_u32_e32 v0, v3
	v_sub_u32_e32 v5, 0, v3
	v_rcp_iflag_f32_e32 v0, v0
	s_nop 0
	v_mul_f32_e32 v0, 0x4f7ffffe, v0
	v_cvt_u32_f32_e32 v0, v0
	v_mul_lo_u32 v5, v5, v0
	v_mul_hi_u32 v5, v0, v5
	v_add_u32_e32 v0, v0, v5
	s_waitcnt vmcnt(0)
	v_mul_hi_u32 v0, v4, v0
	v_mul_lo_u32 v5, v0, v3
	v_sub_u32_e32 v5, v4, v5
	v_add_u32_e32 v6, 1, v0
	v_cmp_ge_u32_e32 vcc, v5, v3
	v_add_u32_e32 v4, 1, v4
	s_nop 0
	v_cndmask_b32_e32 v0, v0, v6, vcc
	v_sub_u32_e32 v6, v5, v3
	v_cndmask_b32_e32 v5, v5, v6, vcc
	v_add_u32_e32 v6, 1, v0
	v_cmp_ge_u32_e32 vcc, v5, v3
	s_nop 1
	v_cndmask_b32_e32 v0, v0, v6, vcc
	v_mul_lo_u32 v5, v3, v0
	v_add_u32_e32 v3, v5, v3
	v_cmp_ne_u32_e32 vcc, v4, v3
	s_and_saveexec_b64 s[2:3], vcc
	s_xor_b64 s[16:17], exec, s[2:3]
	s_cbranch_execz .LBB0_646
	s_waitcnt lgkmcnt(0)
	v_readlane_b32 s98, v247, 3
	v_readlane_b32 s99, v247, 4
	s_nop 4
	global_load_dword v2, v1, s[98:99] sc1
	s_waitcnt vmcnt(0)
	v_cmp_eq_u32_e32 vcc, v2, v0
	s_and_saveexec_b64 s[34:35], vcc
	s_cbranch_execz .LBB0_645
	s_mov_b32 s2, 1
	s_mov_b64 s[40:41], 0
	s_branch .LBB0_636

; __device__ __forceinline__ unsigned xb_ld(unsigned* p)              { return __hip_atomic_load(p, __ATOMIC_RELAXED, __HIP_MEMORY_SCOPE_AGENT); }
; #define XB_SPIN(cond, bar) do { unsigned _sp = 0; while (cond) { __builtin_amdgcn_s_sleep(1); \
;     if ((++_sp & 255u) == 0u) { if (xb_ld(&(bar)[XB_TMO])) break; if (_sp > XB_SPIN_CAP) { atomicAdd(&(bar)[XB_TMO], 1u); break; } } } } while (0)
; __device__ __forceinline__ void xcd_barrier(const XcdBarrier& b) {
;     ...
;             XB_SPIN(xb_ld(&bar[XB_XGEN(b.x)]) == gen, bar);
;             __builtin_amdgcn_fence(__ATOMIC_ACQUIRE, "agent");
.LBB0_638:
	global_load_dword v2, v1, s[98:99] sc1
	s_add_i32 s2, s2, 1
	s_mov_b64 s[46:47], -1
	s_waitcnt vmcnt(0)
	v_cmp_ne_u32_e32 vcc, v2, v0
	s_orn2_b64 s[44:45], vcc, exec
	s_branch .LBB0_635

; __device__ __forceinline__ unsigned xb_ld(unsigned* p)              { return __hip_atomic_load(p, __ATOMIC_RELAXED, __HIP_MEMORY_SCOPE_AGENT); }
; __device__ __forceinline__ unsigned xb_add(unsigned* p, unsigned v) { return __hip_atomic_fetch_add(p, v, __ATOMIC_RELAXED, __HIP_MEMORY_SCOPE_AGENT); }
; #define XB_SPIN(cond, bar) do { unsigned _sp = 0; while (cond) { __builtin_amdgcn_s_sleep(1); \
;     if ((++_sp & 255u) == 0u) { if (xb_ld(&(bar)[XB_TMO])) break; if (_sp > XB_SPIN_CAP) { atomicAdd(&(bar)[XB_TMO], 1u); break; } } } } while (0)
; __device__ __forceinline__ void xcd_barrier(const XcdBarrier& b) {
;     ...
;             if (og + 1u == (tg + 1u) * nx) xb_add(&bar[XB_TOPGEN], 1u);
;             else XB_SPIN(xb_ld(&bar[XB_TOPGEN]) == tg, bar);
;             __builtin_amdgcn_fence(__ATOMIC_ACQUIRE, "agent");
;             xb_add(&bar[XB_XGEN(b.x)], 1u);
;             asm volatile("s_waitcnt vmcnt(0)" ::: "memory");
.LBB0_661:
	s_or_b64 exec, exec, s[34:35]
	s_and_saveexec_b64 s[34:35], s[40:41]
	s_cbranch_execz .LBB0_663
	global_atomic_add v[2:3], v220, off
.LBB0_663:
	s_or_b64 exec, exec, s[34:35]
	s_waitcnt vmcnt(0)
	buffer_inv sc1
	s_waitcnt vmcnt(0)
.LBB0_664:
	s_or_b64 exec, exec, s[16:17]
